# scan phase: the wait for the previous batch's stores at the top of the chunk loop removed (only stores are outstanding there; every load of the batch is consumed behind its own counted wait)
# speedup vs baseline: 1.0047x; 1.0034x over previous
.LBB0_92:
	v_lshl_add_u64 v[30:31], s[26:27], 0, v[2:3]
	v_add_co_u32_e32 v8, vcc, 0x1742c000, v30
	v_lshl_add_u64 v[12:13], s[26:27], 0, v[4:5]
	v_addc_co_u32_e32 v9, vcc, 0, v31, vcc
	v_add_co_u32_e32 v10, vcc, 0x1744c000, v30
	global_load_dword v1, v[8:9], off
	s_nop 0
	v_addc_co_u32_e32 v11, vcc, 0, v31, vcc
	v_add_co_u32_e32 v14, vcc, 0x1746c000, v30
	global_load_dword v58, v[10:11], off
	s_nop 0
	v_addc_co_u32_e32 v15, vcc, 0, v31, vcc
	v_add_co_u32_e32 v16, vcc, 0x1748c000, v30
	global_load_dword v59, v[14:15], off
	s_nop 0
	v_addc_co_u32_e32 v17, vcc, 0, v31, vcc
	v_add_co_u32_e32 v18, vcc, 0x174ac000, v30
	global_load_dword v60, v[16:17], off
	s_nop 0
	v_addc_co_u32_e32 v19, vcc, 0, v31, vcc
	v_add_co_u32_e32 v20, vcc, 0x174cc000, v30
	global_load_dword v61, v[18:19], off
	s_nop 0
	v_addc_co_u32_e32 v21, vcc, 0, v31, vcc
	v_add_co_u32_e32 v22, vcc, 0x174ec000, v30
	global_load_dword v62, v[20:21], off
	s_nop 0
	v_addc_co_u32_e32 v23, vcc, 0, v31, vcc
	v_add_co_u32_e32 v24, vcc, 0x1750c000, v30
	global_load_dword v63, v[22:23], off
	s_nop 0
	v_addc_co_u32_e32 v25, vcc, 0, v31, vcc
	v_add_co_u32_e32 v26, vcc, 0x1752c000, v30
	global_load_dword v64, v[24:25], off
	s_nop 0
	v_addc_co_u32_e32 v27, vcc, 0, v31, vcc
	v_add_co_u32_e32 v28, vcc, 0x1754c000, v30
	global_load_dword v65, v[26:27], off
	s_nop 0
	v_addc_co_u32_e32 v29, vcc, 0, v31, vcc
	v_add_co_u32_e32 v36, vcc, 0x1756c000, v30
	global_load_dword v66, v[28:29], off
	s_nop 0
	v_addc_co_u32_e32 v37, vcc, 0, v31, vcc
	v_add_co_u32_e32 v42, vcc, 0x1758c000, v30
	global_load_dword v67, v[36:37], off
	s_nop 0
	v_addc_co_u32_e32 v43, vcc, 0, v31, vcc
	v_add_co_u32_e32 v38, vcc, 0x175ac000, v30
	global_load_dword v68, v[42:43], off
	s_nop 0
	v_addc_co_u32_e32 v39, vcc, 0, v31, vcc
	v_add_co_u32_e32 v34, vcc, 0x175cc000, v30
	global_load_dword v69, v[38:39], off
	s_nop 0
	v_addc_co_u32_e32 v35, vcc, 0, v31, vcc
	v_add_co_u32_e32 v32, vcc, 0x175ec000, v30
	global_load_dword v70, v[34:35], off
	s_nop 0
	v_addc_co_u32_e32 v33, vcc, 0, v31, vcc
	v_add_co_u32_e32 v30, vcc, 0x1760c000, v30
	global_load_dword v71, v[32:33], off
	s_nop 0
	v_addc_co_u32_e32 v31, vcc, 0, v31, vcc
	v_add_co_u32_e32 v44, vcc, 0x1b42c000, v12
	global_load_dword v72, v[30:31], off
	s_nop 0
	v_addc_co_u32_e32 v45, vcc, 0, v13, vcc
	global_load_dwordx2 v[46:47], v[44:45], off
	s_nop 0
	global_load_dwordx2 v[44:45], v[44:45], off offset:2048
	v_add_co_u32_e32 v48, vcc, 0x1b42d000, v12
	s_waitcnt vmcnt(17)
	v_cvt_f32_f16_e32 v56, v1
	v_addc_co_u32_e32 v49, vcc, 0, v13, vcc
	global_load_dwordx2 v[50:51], v[48:49], off
	s_nop 0
	global_load_dwordx2 v[48:49], v[48:49], off offset:2048
	v_add_co_u32_e32 v52, vcc, 0x1b42e000, v12
	v_cvt_f32_f16_sdwa v57, v1 dst_sel:DWORD dst_unused:UNUSED_PAD src0_sel:WORD_1
	s_nop 0
	v_addc_co_u32_e32 v53, vcc, 0, v13, vcc
	global_load_dwordx2 v[54:55], v[52:53], off
	v_cvt_pk_f16_f32 v73, v6, v7
	s_mov_b32 s3, 0x1b42f000
	s_mov_b64 s[10:11], 0x8000
	v_lshl_add_u64 v[4:5], v[4:5], 0, s[10:11]
	s_add_i32 s2, s2, 16
	s_mov_b64 s[10:11], 0x200000
	v_lshl_add_u64 v[2:3], v[2:3], 0, s[10:11]
	s_cmpk_gt_u32 s2, 0xef
	s_waitcnt vmcnt(4)
	v_pk_fma_f32 v[6:7], v[6:7], v[46:47], v[56:57]
	v_cvt_f32_f16_e32 v46, v58
	v_cvt_f32_f16_sdwa v47, v58 dst_sel:DWORD dst_unused:UNUSED_PAD src0_sel:WORD_1
	v_cvt_pk_f16_f32 v1, v6, v7
	s_waitcnt vmcnt(3)
	v_pk_fma_f32 v[6:7], v[6:7], v[44:45], v[46:47]
	v_cvt_f32_f16_e32 v44, v59
	v_cvt_f32_f16_sdwa v45, v59 dst_sel:DWORD dst_unused:UNUSED_PAD src0_sel:WORD_1
	v_cvt_pk_f16_f32 v56, v6, v7
	v_add_co_u32_e32 v46, vcc, s3, v12
	s_waitcnt vmcnt(2)
	v_pk_fma_f32 v[6:7], v[6:7], v[50:51], v[44:45]
	v_cvt_f32_f16_e32 v44, v60
	v_cvt_f32_f16_sdwa v45, v60 dst_sel:DWORD dst_unused:UNUSED_PAD src0_sel:WORD_1
	v_cvt_pk_f16_f32 v57, v6, v7
	v_addc_co_u32_e32 v47, vcc, 0, v13, vcc
	s_waitcnt vmcnt(1)
	v_pk_fma_f32 v[6:7], v[6:7], v[48:49], v[44:45]
	v_cvt_f32_f16_e32 v44, v61
	v_cvt_f32_f16_sdwa v45, v61 dst_sel:DWORD dst_unused:UNUSED_PAD src0_sel:WORD_1
	v_cvt_pk_f16_f32 v58, v6, v7
	s_mov_b32 s3, 0x1b430000
	v_add_co_u32_e32 v48, vcc, s3, v12
	s_waitcnt vmcnt(0)
	v_pk_fma_f32 v[6:7], v[6:7], v[54:55], v[44:45]
	global_load_dwordx2 v[44:45], v[52:53], off offset:2048
	v_addc_co_u32_e32 v49, vcc, 0, v13, vcc
	global_load_dwordx2 v[50:51], v[48:49], off offset:-4096
	s_nop 0
	global_load_dwordx2 v[46:47], v[46:47], off offset:2048
	s_nop 0
	global_load_dwordx2 v[52:53], v[48:49], off
	s_nop 0
	global_load_dwordx2 v[48:49], v[48:49], off offset:2048
	v_cvt_f32_f16_e32 v54, v62
	v_cvt_f32_f16_sdwa v55, v62 dst_sel:DWORD dst_unused:UNUSED_PAD src0_sel:WORD_1
	v_cvt_pk_f16_f32 v59, v6, v7
	s_mov_b32 s3, 0x1b431000
	s_waitcnt vmcnt(4)
	v_pk_fma_f32 v[6:7], v[6:7], v[44:45], v[54:55]
	v_cvt_f32_f16_e32 v44, v63
	v_cvt_f32_f16_sdwa v45, v63 dst_sel:DWORD dst_unused:UNUSED_PAD src0_sel:WORD_1
	v_cvt_pk_f16_f32 v60, v6, v7
	s_waitcnt vmcnt(3)
	v_pk_fma_f32 v[6:7], v[6:7], v[50:51], v[44:45]
	v_cvt_f32_f16_e32 v44, v64
	v_cvt_f32_f16_sdwa v45, v64 dst_sel:DWORD dst_unused:UNUSED_PAD src0_sel:WORD_1
	v_cvt_pk_f16_f32 v61, v6, v7
	v_cvt_f32_f16_e32 v50, v67
	v_cvt_f32_f16_sdwa v51, v67 dst_sel:DWORD dst_unused:UNUSED_PAD src0_sel:WORD_1
	s_waitcnt vmcnt(2)
	v_pk_fma_f32 v[6:7], v[6:7], v[46:47], v[44:45]
	v_cvt_f32_f16_e32 v44, v65
	v_cvt_f32_f16_sdwa v45, v65 dst_sel:DWORD dst_unused:UNUSED_PAD src0_sel:WORD_1
	v_cvt_pk_f16_f32 v62, v6, v7
	s_waitcnt vmcnt(1)
	v_pk_fma_f32 v[6:7], v[6:7], v[52:53], v[44:45]
	v_cvt_f32_f16_e32 v44, v66
	v_cvt_f32_f16_sdwa v45, v66 dst_sel:DWORD dst_unused:UNUSED_PAD src0_sel:WORD_1
	v_cvt_pk_f16_f32 v63, v6, v7
	s_waitcnt vmcnt(0)
	v_pk_fma_f32 v[6:7], v[6:7], v[48:49], v[44:45]
	v_add_co_u32_e32 v44, vcc, s3, v12
	s_mov_b32 s3, 0x1b432000
	s_nop 0
	v_addc_co_u32_e32 v45, vcc, 0, v13, vcc
	v_add_co_u32_e32 v46, vcc, s3, v12
	s_mov_b32 s3, 0x1b433000
	s_nop 0
	v_addc_co_u32_e32 v47, vcc, 0, v13, vcc
	global_load_dwordx2 v[48:49], v[46:47], off offset:-4096
	s_nop 0
	global_load_dwordx2 v[44:45], v[44:45], off offset:2048
	s_nop 0
	global_load_dwordx2 v[52:53], v[46:47], off
	s_nop 0
	global_load_dwordx2 v[46:47], v[46:47], off offset:2048
	v_add_co_u32_e32 v12, vcc, s3, v12
	v_cvt_pk_f16_f32 v64, v6, v7
	s_nop 0
	v_addc_co_u32_e32 v13, vcc, 0, v13, vcc
	global_load_dwordx2 v[54:55], v[12:13], off
	s_nop 0
	global_load_dwordx2 v[12:13], v[12:13], off offset:2048
	s_nop 0
	global_store_dword v[8:9], v73, off
	global_store_dword v[10:11], v1, off
	global_store_dword v[14:15], v56, off
	global_store_dword v[16:17], v57, off
	global_store_dword v[18:19], v58, off
	global_store_dword v[20:21], v59, off
	global_store_dword v[22:23], v60, off
	global_store_dword v[24:25], v61, off
	global_store_dword v[26:27], v62, off
	global_store_dword v[28:29], v63, off
	global_store_dword v[36:37], v64, off
	v_cvt_f32_f16_e32 v8, v68
	v_cvt_f32_f16_sdwa v9, v68 dst_sel:DWORD dst_unused:UNUSED_PAD src0_sel:WORD_1
	s_waitcnt vmcnt(16)
	v_pk_fma_f32 v[6:7], v[6:7], v[48:49], v[50:51]
	s_nop 0
	v_cvt_pk_f16_f32 v1, v6, v7
	s_waitcnt vmcnt(15)
	v_pk_fma_f32 v[6:7], v[6:7], v[44:45], v[8:9]
	v_cvt_f32_f16_e32 v8, v69
	v_cvt_f32_f16_sdwa v9, v69 dst_sel:DWORD dst_unused:UNUSED_PAD src0_sel:WORD_1
	global_store_dword v[42:43], v1, off
	v_cvt_pk_f16_f32 v1, v6, v7
	global_store_dword v[38:39], v1, off
	s_waitcnt vmcnt(16)
	v_pk_fma_f32 v[6:7], v[6:7], v[52:53], v[8:9]
	v_cvt_f32_f16_e32 v8, v70
	v_cvt_f32_f16_sdwa v9, v70 dst_sel:DWORD dst_unused:UNUSED_PAD src0_sel:WORD_1
	v_cvt_pk_f16_f32 v1, v6, v7
	global_store_dword v[34:35], v1, off
	s_waitcnt vmcnt(16)
	v_pk_fma_f32 v[6:7], v[6:7], v[46:47], v[8:9]
	v_cvt_f32_f16_e32 v8, v71
	v_cvt_f32_f16_sdwa v9, v71 dst_sel:DWORD dst_unused:UNUSED_PAD src0_sel:WORD_1
	v_cvt_pk_f16_f32 v1, v6, v7
	global_store_dword v[32:33], v1, off
	s_waitcnt vmcnt(16)
	v_pk_fma_f32 v[6:7], v[6:7], v[54:55], v[8:9]
	v_cvt_f32_f16_e32 v8, v72
	v_cvt_f32_f16_sdwa v9, v72 dst_sel:DWORD dst_unused:UNUSED_PAD src0_sel:WORD_1
	v_cvt_pk_f16_f32 v1, v6, v7
	global_store_dword v[30:31], v1, off
	s_waitcnt vmcnt(16)
	v_pk_fma_f32 v[6:7], v[6:7], v[12:13], v[8:9]
	s_cbranch_scc0 .LBB0_92
	v_readlane_b32 s2, v254, 23
	s_nop 1
	v_add_u32_e32 v40, s2, v40
	s_movk_i32 s2, 0x7fff
	v_cmp_lt_i32_e32 vcc, s2, v40
	v_readlane_b32 s2, v255, 26
	s_or_b64 s[8:9], vcc, s[8:9]
	s_nop 0
	v_add_u32_e32 v0, s2, v0
	s_andn2_b64 exec, exec, s[8:9]
	s_cbranch_execnz .LBB0_91
